# k10 + diff tile loop branch layout: tile-0 PADMASK block moved out of line, single conditional back edge (two fewer taken branches per tile)
# baseline (speedup 1.0000x reference)
.LBB0_399:
	s_cmp_ge_i32 s56, s94
	s_cbranch_scc1 .LBB0_405
	ds_read_b128 v[128:131], v201 offset:0
	ds_read_b128 v[148:151], v201 offset:0x2000
	ds_read_b128 v[216:219], v203 offset:0
	ds_read_b128 v[220:223], v203 offset:0x2000
	s_waitcnt lgkmcnt(2)
	s_nop 0
	v_mfma_f32_32x32x16_bf16 v[128:143], v[128:131], v[160:163], 0
	v_mfma_f32_32x32x16_bf16 v[144:159], v[148:151], v[160:163], 0
	ds_read_b128 v[224:227], v206 offset:0
	ds_read_b128 v[228:231], v206 offset:0x2000
	s_waitcnt lgkmcnt(2)
	v_mfma_f32_32x32x16_bf16 v[128:143], v[216:219], v[164:167], v[128:143]
	v_mfma_f32_32x32x16_bf16 v[144:159], v[220:223], v[164:167], v[144:159]
	ds_read_b128 v[216:219], v208 offset:0
	ds_read_b128 v[220:223], v208 offset:0x2000
	s_waitcnt lgkmcnt(2)
	v_mfma_f32_32x32x16_bf16 v[128:143], v[224:227], v[168:171], v[128:143]
	v_mfma_f32_32x32x16_bf16 v[144:159], v[228:231], v[168:171], v[144:159]
	ds_read_b128 v[224:227], v201 offset:0x80
	ds_read_b128 v[228:231], v201 offset:0x2080
	s_waitcnt lgkmcnt(2)
	v_mfma_f32_32x32x16_bf16 v[128:143], v[216:219], v[172:175], v[128:143]
	v_mfma_f32_32x32x16_bf16 v[144:159], v[220:223], v[172:175], v[144:159]
	ds_read_b128 v[216:219], v203 offset:0x80
	ds_read_b128 v[220:223], v203 offset:0x2080
	s_waitcnt lgkmcnt(2)
	v_mfma_f32_32x32x16_bf16 v[128:143], v[224:227], v[176:179], v[128:143]
	v_mfma_f32_32x32x16_bf16 v[144:159], v[228:231], v[176:179], v[144:159]
	ds_read_b128 v[224:227], v206 offset:0x80
	ds_read_b128 v[228:231], v206 offset:0x2080
	s_waitcnt lgkmcnt(2)
	v_mfma_f32_32x32x16_bf16 v[128:143], v[216:219], v[180:183], v[128:143]
	v_mfma_f32_32x32x16_bf16 v[144:159], v[220:223], v[180:183], v[144:159]
	ds_read_b128 v[216:219], v208 offset:0x80
	ds_read_b128 v[220:223], v208 offset:0x2080
	s_waitcnt lgkmcnt(2)
	v_mfma_f32_32x32x16_bf16 v[128:143], v[224:227], v[240:243], v[128:143]
	v_mfma_f32_32x32x16_bf16 v[144:159], v[228:231], v[240:243], v[144:159]
	s_waitcnt lgkmcnt(0)
	v_mfma_f32_32x32x16_bf16 v[128:143], v[216:219], v[244:247], v[128:143]
	s_cmp_eq_u32 s56, 0
	s_cselect_b64 vcc, -1, 0
	s_mov_b32 s14, 0x41000000
	v_mfma_f32_32x32x16_bf16 v[144:159], v[220:223], v[244:247], v[144:159]
	s_cbranch_scc1 .Ldiff_pad
	s_nop 7
	v_max_f32_e32 v215, v128, v129
	v_max3_f32 v215, v215, v130, v131
	v_max3_f32 v215, v215, v132, v133
	v_max3_f32 v215, v215, v134, v135
	v_max3_f32 v215, v215, v136, v137
	v_max3_f32 v215, v215, v138, v139
	v_max3_f32 v215, v215, v140, v141
	v_max3_f32 v215, v215, v142, v143
	v_max3_f32 v215, v215, v144, v145
	v_max3_f32 v215, v215, v146, v147
	v_max3_f32 v215, v215, v148, v149
	v_max3_f32 v215, v215, v150, v151
	v_max3_f32 v215, v215, v152, v153
	v_max3_f32 v215, v215, v154, v155
	v_max3_f32 v215, v215, v156, v157
	v_max3_f32 v215, v215, v158, v159
.Ldiff_padjoin:
	v_mov_b32_e32 v216, v215
	s_nop 1
	v_permlane32_swap_b32_e32 v215, v216
	v_max_f32_e32 v215, v215, v216
	v_sub_f32_e32 v216, v215, v210
	v_mul_f32_e32 v216, 0x3db504f3, v216
	v_cmp_ge_f32_e32 vcc, s14, v216
	v_mul_f32_e32 v216, 0xbe0293ee, v210
	s_cmp_eq_u64 vcc, exec
	s_cbranch_scc0 .Ldiff_sm_rare
	v_fmamk_f32 v128, v128, 0x3e0293ee, v216
	v_fmamk_f32 v129, v129, 0x3e0293ee, v216
	v_exp_f32_e32 v128, v128
	v_fmamk_f32 v130, v130, 0x3e0293ee, v216
	v_exp_f32_e32 v129, v129
	v_fmamk_f32 v131, v131, 0x3e0293ee, v216
	v_exp_f32_e32 v130, v130
	v_fmamk_f32 v132, v132, 0x3e0293ee, v216
	v_fmamk_f32 v133, v133, 0x3e0293ee, v216
	v_fmamk_f32 v134, v134, 0x3e0293ee, v216
	v_fmamk_f32 v135, v135, 0x3e0293ee, v216
	v_fmamk_f32 v136, v136, 0x3e0293ee, v216
	v_fmamk_f32 v137, v137, 0x3e0293ee, v216
	v_fmamk_f32 v138, v138, 0x3e0293ee, v216
	v_fmamk_f32 v139, v139, 0x3e0293ee, v216
	v_fmamk_f32 v140, v140, 0x3e0293ee, v216
	v_fmamk_f32 v141, v141, 0x3e0293ee, v216
	v_fmamk_f32 v142, v142, 0x3e0293ee, v216
	v_fmamk_f32 v143, v143, 0x3e0293ee, v216
	v_fmamk_f32 v144, v144, 0x3e0293ee, v216
	v_fmamk_f32 v145, v145, 0x3e0293ee, v216
	v_fmamk_f32 v146, v146, 0x3e0293ee, v216
	v_fmamk_f32 v147, v147, 0x3e0293ee, v216
	v_fmamk_f32 v148, v148, 0x3e0293ee, v216
	v_fmamk_f32 v149, v149, 0x3e0293ee, v216
	v_fmamk_f32 v150, v150, 0x3e0293ee, v216
	v_fmamk_f32 v151, v151, 0x3e0293ee, v216
	v_fmamk_f32 v152, v152, 0x3e0293ee, v216
	v_fmamk_f32 v153, v153, 0x3e0293ee, v216
	v_fmamk_f32 v154, v154, 0x3e0293ee, v216
	v_fmamk_f32 v155, v155, 0x3e0293ee, v216
	v_fmamk_f32 v156, v156, 0x3e0293ee, v216
	v_fmamk_f32 v157, v157, 0x3e0293ee, v216
	v_fmamk_f32 v158, v158, 0x3e0293ee, v216
	v_fmac_f32_e32 v216, 0x3e0293ee, v159
	v_exp_f32_e32 v131, v131
	v_exp_f32_e32 v132, v132
	v_exp_f32_e32 v159, v216
	v_add_f32_e32 v216, 0, v128
	v_exp_f32_e32 v133, v133
	v_add_f32_e32 v216, v129, v216
	v_exp_f32_e32 v134, v134
	v_add_f32_e32 v216, v130, v216
	v_exp_f32_e32 v135, v135
	v_add_f32_e32 v216, v131, v216
	v_exp_f32_e32 v136, v136
	v_add_f32_e32 v216, v132, v216
	v_exp_f32_e32 v137, v137
	v_add_f32_e32 v216, v133, v216
	v_exp_f32_e32 v138, v138
	v_add_f32_e32 v216, v134, v216
	v_exp_f32_e32 v139, v139
	v_add_f32_e32 v216, v135, v216
	v_exp_f32_e32 v140, v140
	v_add_f32_e32 v216, v136, v216
	v_exp_f32_e32 v141, v141
	v_add_f32_e32 v216, v137, v216
	v_exp_f32_e32 v142, v142
	v_add_f32_e32 v216, v138, v216
	v_exp_f32_e32 v143, v143
	v_add_f32_e32 v216, v139, v216
	v_exp_f32_e32 v144, v144
	v_add_f32_e32 v216, v140, v216
	v_exp_f32_e32 v145, v145
	v_add_f32_e32 v216, v141, v216
	v_exp_f32_e32 v146, v146
	v_add_f32_e32 v216, v142, v216
	v_exp_f32_e32 v147, v147
	v_add_f32_e32 v216, v143, v216
	v_exp_f32_e32 v148, v148
	v_add_f32_e32 v216, v144, v216
	v_exp_f32_e32 v149, v149
	v_add_f32_e32 v216, v145, v216
	v_exp_f32_e32 v150, v150
	v_add_f32_e32 v216, v146, v216
	v_exp_f32_e32 v151, v151
	v_add_f32_e32 v216, v147, v216
	v_exp_f32_e32 v152, v152
	v_add_f32_e32 v216, v148, v216
	v_exp_f32_e32 v153, v153
	v_add_f32_e32 v216, v149, v216
	v_exp_f32_e32 v154, v154
	v_add_f32_e32 v216, v150, v216
	v_exp_f32_e32 v155, v155
	v_add_f32_e32 v216, v151, v216
	v_exp_f32_e32 v156, v156
	v_add_f32_e32 v216, v152, v216
	v_exp_f32_e32 v157, v157
	v_add_f32_e32 v216, v153, v216
	v_exp_f32_e32 v158, v158
	v_add_f32_e32 v216, v154, v216
	v_add_f32_e32 v216, v155, v216
	v_add_f32_e32 v216, v156, v216
	v_add_f32_e32 v216, v157, v216
	v_add_f32_e32 v216, v158, v216
	v_add_f32_e32 v216, v159, v216
	v_mov_b32_e32 v217, v216
	v_cvt_pk_bf16_f32 v128, v128, v129
	v_cvt_pk_bf16_f32 v129, v130, v131
	v_cvt_pk_bf16_f32 v130, v132, v133
	v_cvt_pk_bf16_f32 v131, v134, v135
	v_cvt_pk_bf16_f32 v132, v136, v137
	v_cvt_pk_bf16_f32 v133, v138, v139
	v_cvt_pk_bf16_f32 v134, v140, v141
	v_cvt_pk_bf16_f32 v135, v142, v143
	v_cvt_pk_bf16_f32 v136, v144, v145
	v_cvt_pk_bf16_f32 v137, v146, v147
	v_cvt_pk_bf16_f32 v138, v148, v149
	v_cvt_pk_bf16_f32 v139, v150, v151
	v_cvt_pk_bf16_f32 v140, v152, v153
	v_cvt_pk_bf16_f32 v141, v154, v155
	v_cvt_pk_bf16_f32 v142, v156, v157
	v_cvt_pk_bf16_f32 v143, v158, v159
	s_nop 1
	v_permlane32_swap_b32_e32 v216, v217
	v_add_f32_e32 v230, v216, v217
	v_add_f32_e32 v230, v214, v230

.LBB0_405:
	v_xor_b32_e32 v200, 0xc000, v200
	v_xor_b32_e32 v201, 0x1c000, v201
	v_xor_b32_e32 v203, 0x1c000, v203
	v_xor_b32_e32 v206, 0x1c000, v206
	v_xor_b32_e32 v208, 0x1c000, v208
	s_add_i32 s44, s44, 64
	s_mov_b32 s56, s96
	s_cmp_lg_u32 s95, s96
	s_cbranch_scc1 .LBB0_397
	s_branch .LBB0_407
.Ldiff_pad:
	s_nop 7
	v_max_f32_e32 v215, v128, v129
	v_max3_f32 v215, v215, v130, v131
	v_max3_f32 v215, v215, v132, v133
	v_cndmask_b32_e32 v137, v137, v193, vcc
	v_cndmask_b32_e32 v136, v136, v193, vcc
	v_max3_f32 v215, v215, v134, v135
	v_cndmask_b32_e32 v139, v139, v193, vcc
	v_cndmask_b32_e32 v138, v138, v193, vcc
	v_max3_f32 v215, v215, v136, v137
	v_cndmask_b32_e32 v141, v141, v193, vcc
	v_cndmask_b32_e32 v140, v140, v193, vcc
	v_max3_f32 v215, v215, v138, v139
	v_cndmask_b32_e32 v143, v143, v193, vcc
	v_cndmask_b32_e32 v142, v142, v193, vcc
	v_max3_f32 v215, v215, v140, v141
	v_cndmask_b32_e32 v145, v145, v193, vcc
	v_cndmask_b32_e32 v144, v144, v193, vcc
	v_max3_f32 v215, v215, v142, v143
	v_cndmask_b32_e32 v147, v147, v193, vcc
	v_cndmask_b32_e32 v146, v146, v193, vcc
	v_max3_f32 v215, v215, v144, v145
	v_cndmask_b32_e32 v149, v149, v193, vcc
	v_cndmask_b32_e32 v148, v148, v193, vcc
	v_max3_f32 v215, v215, v146, v147
	v_cndmask_b32_e32 v151, v151, v193, vcc
	v_cndmask_b32_e32 v150, v150, v193, vcc
	v_max3_f32 v215, v215, v148, v149
	v_cndmask_b32_e32 v153, v153, v193, vcc
	v_cndmask_b32_e32 v152, v152, v193, vcc
	v_max3_f32 v215, v215, v150, v151
	v_cndmask_b32_e32 v155, v155, v193, vcc
	v_cndmask_b32_e32 v154, v154, v193, vcc
	v_max3_f32 v215, v215, v152, v153
	v_cndmask_b32_e32 v157, v157, v193, vcc
	v_cndmask_b32_e32 v156, v156, v193, vcc
	v_max3_f32 v215, v215, v154, v155
	v_cndmask_b32_e32 v159, v159, v193, vcc
	v_cndmask_b32_e32 v158, v158, v193, vcc
	v_max3_f32 v215, v215, v156, v157
	v_max3_f32 v215, v215, v158, v159
	s_branch .Ldiff_padjoin
